# P7 epilogue: wave owns 64 contiguous cols (B LDS row remap) + DPP row_ror:8 half exchange so each store writes 8 rows x 128B
# speedup vs baseline: 1.0035x; 1.0035x over previous
; #define G8_STAGE(bufoff, gbase, NM) do { _Pragma("unroll") for (int _i = 0; _i < 2; ++_i) { \
;     const char* _b = (const char*)(gbase) + (_i ? p2##NM : (size_t)0); asm volatile("" : "+s"(_b));     \
;     __builtin_amdgcn_global_load_lds((const unsigned*)(_b + voff##NM), (LAS unsigned*)(lds + (bufoff) + ldsw + _i * 8192), 16, 0, 0); } } while (0)
; #define G8_WAIT_V(n) asm volatile("s_waitcnt vmcnt(" #n ")" ::: "memory")
; #define G8_BAR __builtin_amdgcn_s_barrier()
;     ...
;   const int wid = __builtin_amdgcn_readfirstlane(tid >> 6), lane = tid & 63, wr = wid >> 2, wc = wid & 3, fr = lane & 15, fq = lane >> 4;
;   const int nt = K / BK;
;   unsigned voffA, voffB;
;   { int R, C; stage_rc(tid * 16, R, C); const int Rb = (R & ~31) + perm32(R & 31); voffA = (unsigned)(R * lda + C) * 2u; voffB = (unsigned)(Rb * ldb + C) * 2u; }
;   const size_t p2A = (size_t)64 * lda * 2, p2B = (size_t)64 * ldb * 2;
;   const size_t kstep = (size_t)(BK * 2);
;   const size_t hstepA = (size_t)HALF * lda * 2, hstepB = (size_t)HALF * ldb * 2;
;   const unsigned ldsw = (unsigned)wid * 1024u;
;   const int aoff = lds_byte(wr * 64 + fr, fq * 8), boff = lds_byte(wc * 32 + fr, fq * 8);
;     ...
;   G8_WAIT_V(2); G8_BAR;
;   G8_STAGE(G8_SB(1, 0), cB + kstep, B); G8_STAGE(G8_SA(1, 0), cA + kstep, A); G8_STAGE(G8_SB(1, 1), cB + hstepB + kstep, B);
;   G8_WAIT_V(6); G8_BAR;
.LBB0_1115:
	s_lshl_b32 s12, s12, 12
	s_lshl_b32 s14, s13, 13
	s_lshl_b32 s15, s12, 1
	s_and_b32 s15, s15, 0x6000
	s_add_u32 s12, s26, 0x80
	s_addc_u32 s13, s27, 0
	s_waitcnt vmcnt(2)
	s_barrier
	s_add_i32 m0, s1, 0x18000
	v_and_b32_e32 v1, 15, v0
	v_lshl_add_u64 v[2:3], s[12:13], 0, v[130:131]
	s_add_u32 s12, s26, 0x42080
	s_addc_u32 s13, s27, 0
	global_load_lds_dwordx4 v[2:3], off
	s_add_i32 m0, s1, 0x1a000
	v_lshl_add_u64 v[2:3], s[12:13], 0, v[130:131]
	s_add_u32 s12, s4, 0x80
	s_addc_u32 s13, s5, 0
	global_load_lds_dwordx4 v[2:3], off
	s_add_i32 s37, s1, 0x8000
	v_lshl_add_u64 v[2:3], s[12:13], 0, v[128:129]
	s_add_u32 s12, s4, 0x42080
	s_mov_b32 m0, s37
	s_addc_u32 s13, s5, 0
	global_load_lds_dwordx4 v[2:3], off
	s_add_i32 s38, s1, 0xa000
	v_lshl_add_u64 v[2:3], s[12:13], 0, v[128:129]
	s_add_u32 s12, s26, 0x84080
	s_mov_b32 m0, s38
	s_addc_u32 s13, s27, 0
	global_load_lds_dwordx4 v[2:3], off
	s_add_i32 m0, s1, 0x1c000
	v_lshlrev_b32_e32 v1, 6, v1
	v_lshl_add_u64 v[2:3], s[12:13], 0, v[130:131]
	s_add_u32 s12, s26, 0xc6080
	s_addc_u32 s13, s27, 0
	global_load_lds_dwordx4 v[2:3], off
	s_add_i32 m0, s1, 0x1e000
	v_lshl_add_u64 v[2:3], s[12:13], 0, v[130:131]
	global_load_lds_dwordx4 v[2:3], off
	v_and_b32_e32 v2, 48, v0
	v_lshlrev_b32_e32 v0, 2, v0
	v_and_b32_e32 v0, 32, v0
	v_or_b32_e32 v3, v1, v2
	v_bitop3_b32 v1, v1, v0, v2 bitop3:0x36
	s_waitcnt vmcnt(6)
	s_cmpk_lt_u32 s6, 0x100
	v_bitop3_b32 v0, v3, s14, v0 bitop3:0xde
	v_or_b32_e32 v140, s15, v1
	s_cselect_b64 s[12:13], -1, 0
	s_add_i32 s39, 0, 0x10000
	s_add_i32 s40, 0, 0x14000
	s_sext_i32_i8 s49, s7
	v_add_u32_e32 v141, s39, v140
	v_add_u32_e32 v142, 0x1000, v141
	v_add_u32_e32 v143, 0, v0
	v_mov_b32_e32 v144, 0x358637bd
	s_mov_b32 s41, 0x800000
	s_mov_b64 s[14:15], 0x100000
	s_mov_b32 s42, 0x100000
	s_mov_b64 s[16:17], 0x120000
	s_mov_b32 s43, 0x120000
	s_mov_b64 s[18:19], 0x140000
	s_mov_b32 s44, 0x140000
	s_mov_b64 s[20:21], 0x160000
	s_mov_b32 s45, 0x160000
	s_mov_b64 s[22:23], s[4:5]
	s_mov_b64 s[24:25], s[26:27]
	s_barrier
	s_branch .LBB0_1118

; #define G8_STAGE(bufoff, gbase, NM) do { _Pragma("unroll") for (int _i = 0; _i < 2; ++_i) { \
;     const char* _b = (const char*)(gbase) + (_i ? p2##NM : (size_t)0); asm volatile("" : "+s"(_b));     \
;     __builtin_amdgcn_global_load_lds((const unsigned*)(_b + voff##NM), (LAS unsigned*)(lds + (bufoff) + ldsw + _i * 8192), 16, 0, 0); } } while (0)
; #define G8_WAIT_V(n) asm volatile("s_waitcnt vmcnt(" #n ")" ::: "memory")
; #define G8_WAIT_L(n) asm volatile("s_waitcnt lgkmcnt(" #n ")" ::: "memory")
; #define G8_BAR __builtin_amdgcn_s_barrier()
; #define G8_SCHED __builtin_amdgcn_sched_barrier(0)
;     ...
;     for (int t = 0; t < nt; t += 2) {
;       const bool last = (t == nt - 2);
;       const char* a1 = cA + (size_t)(t + 1) * kstep + hstepA;
;       const char* a2 = last ? nA : cA + (size_t)(t + 2) * kstep; const char* b2 = last ? nB : cB + (size_t)(t + 2) * kstep;
;       const char* a3 = a2 + kstep; const char* b3 = b2 + kstep;
;       asm volatile("" : "+s"(a1), "+s"(a2), "+s"(b2), "+s"(a3), "+s"(b3));
;       G8_LDB(B0, 0, 0); G8_LDB(B1, 0, 1); G8_SCHED; G8_LDA(At, 0, 0); G8_STAGE(G8_SA(1, 1), a1, A);
;       const bool d0a = (BD == 0) || (BD == 1 && t < (nt >> 1)) || (BD == 2 && !(cur.pn & 1));
;       const bool d1a = (BD == 0) || (BD == 1 && t >= (nt >> 1)) || (BD == 2 && !(cur.pn & 1));
;       const bool d0b = (BD == 0) || (BD == 1 && t < (nt >> 1)) || (BD == 2 && (cur.pn & 1));
;       const bool d1b = (BD == 0) || (BD == 1 && t >= (nt >> 1)) || (BD == 2 && (cur.pn & 1));
;       G8_WAIT_V(8); G8_WAIT_L(0); G8_BAR; if (d0a) G8_MMA(0, 0, At, B0); if (d1a) G8_MMA(0, 1, At, B1); G8_BAR; G8_SCHED;
;       G8_LDA(At, 0, 1); G8_STAGE(G8_SB(0, 0), b2, B); G8_STAGE(G8_SB(0, 1), b2 + hstepB, B); G8_STAGE(G8_SA(0, 0), a2, A);
;       G8_WAIT_V(8); G8_WAIT_L(0); G8_BAR; if (d0a) G8_MMA(1, 0, At, B0); if (d1a) G8_MMA(1, 1, At, B1); G8_BAR; G8_SCHED;
.LBB0_1125:
	s_cmp_eq_u32 s54, 28
	s_cselect_b32 s30, s22, s50
	s_cselect_b32 s31, s23, s51
	s_cselect_b32 s35, s25, s53
	s_cselect_b32 s34, s24, s52
	s_add_u32 s26, s30, 0x80
	s_addc_u32 s27, s31, 0
	s_add_u32 s28, s34, 0x80
	s_addc_u32 s29, s35, 0
	s_mov_b64 s[56:57], s[4:5]
	ds_read_b128 v[134:137], v141
	ds_read_b128 v[146:149], v141 offset:1024
	ds_read_b128 v[150:153], v141 offset:2048
	ds_read_b128 v[154:157], v141 offset:3072
	ds_read_b128 v[158:161], v142
	ds_read_b128 v[162:165], v142 offset:1024
	ds_read_b128 v[166:169], v142 offset:2048
	ds_read_b128 v[170:173], v142 offset:3072
	s_add_i32 m0, s1, 0xc000
	s_mov_b64 s[58:59], s[56:57]
	s_add_u32 s56, s56, 0x42000
	ds_read_b128 v[174:177], v143
	ds_read_b128 v[178:181], v143 offset:1024
	ds_read_b128 v[182:185], v143 offset:2048
	ds_read_b128 v[186:189], v143 offset:3072
	ds_read_b128 v[190:193], v143 offset:4096
	ds_read_b128 v[194:197], v143 offset:5120
	ds_read_b128 v[202:205], v143 offset:6144
	ds_read_b128 v[206:209], v143 offset:7168
	s_addc_u32 s57, s57, 0
	v_lshl_add_u64 v[138:139], s[58:59], 0, v[128:129]
	global_load_lds_dwordx4 v[138:139], off
	s_add_i32 m0, s1, 0xe000
	v_lshl_add_u64 v[138:139], s[56:57], 0, v[128:129]
	global_load_lds_dwordx4 v[138:139], off
	s_waitcnt vmcnt(8)
	s_waitcnt lgkmcnt(0)
	s_barrier
	s_setprio 1
	s_waitcnt lgkmcnt(0)
	v_mfma_f32_16x16x32_bf16 v[124:127], v[134:137], v[174:177], v[124:127]
	v_mfma_f32_16x16x32_bf16 v[120:123], v[150:153], v[174:177], v[120:123]
	v_mfma_f32_16x16x32_bf16 v[108:111], v[134:137], v[182:185], v[108:111]
	v_mfma_f32_16x16x32_bf16 v[104:107], v[150:153], v[182:185], v[104:107]
	v_mfma_f32_16x16x32_bf16 v[92:95], v[134:137], v[190:193], v[92:95]
	v_mfma_f32_16x16x32_bf16 v[88:91], v[150:153], v[190:193], v[88:91]
	v_mfma_f32_16x16x32_bf16 v[76:79], v[134:137], v[202:205], v[76:79]
	v_mfma_f32_16x16x32_bf16 v[72:75], v[150:153], v[202:205], v[72:75]
	v_mfma_f32_16x16x32_bf16 v[124:127], v[146:149], v[178:181], v[124:127]
	v_mfma_f32_16x16x32_bf16 v[120:123], v[154:157], v[178:181], v[120:123]
	v_mfma_f32_16x16x32_bf16 v[108:111], v[146:149], v[186:189], v[108:111]
	v_mfma_f32_16x16x32_bf16 v[104:107], v[154:157], v[186:189], v[104:107]
	v_mfma_f32_16x16x32_bf16 v[92:95], v[146:149], v[194:197], v[92:95]
	v_mfma_f32_16x16x32_bf16 v[88:91], v[154:157], v[194:197], v[88:91]
	v_mfma_f32_16x16x32_bf16 v[76:79], v[146:149], v[206:209], v[76:79]
	v_mfma_f32_16x16x32_bf16 v[72:75], v[154:157], v[206:209], v[72:75]
	s_setprio 0
	s_setprio 1
	v_mfma_f32_16x16x32_bf16 v[116:119], v[158:161], v[174:177], v[116:119]
	v_mfma_f32_16x16x32_bf16 v[112:115], v[166:169], v[174:177], v[112:115]
	v_mfma_f32_16x16x32_bf16 v[100:103], v[158:161], v[182:185], v[100:103]
	v_mfma_f32_16x16x32_bf16 v[96:99], v[166:169], v[182:185], v[96:99]
	v_mfma_f32_16x16x32_bf16 v[84:87], v[158:161], v[190:193], v[84:87]
	v_mfma_f32_16x16x32_bf16 v[80:83], v[166:169], v[190:193], v[80:83]
	v_mfma_f32_16x16x32_bf16 v[68:71], v[158:161], v[202:205], v[68:71]
	v_mfma_f32_16x16x32_bf16 v[64:67], v[166:169], v[202:205], v[64:67]
	v_mfma_f32_16x16x32_bf16 v[116:119], v[162:165], v[178:181], v[116:119]
	v_mfma_f32_16x16x32_bf16 v[112:115], v[170:173], v[178:181], v[112:115]
	v_mfma_f32_16x16x32_bf16 v[100:103], v[162:165], v[186:189], v[100:103]
	v_mfma_f32_16x16x32_bf16 v[96:99], v[170:173], v[186:189], v[96:99]
	v_mfma_f32_16x16x32_bf16 v[84:87], v[162:165], v[194:197], v[84:87]
	v_mfma_f32_16x16x32_bf16 v[80:83], v[170:173], v[194:197], v[80:83]
	v_mfma_f32_16x16x32_bf16 v[68:71], v[162:165], v[206:209], v[68:71]
	v_mfma_f32_16x16x32_bf16 v[64:67], v[170:173], v[206:209], v[64:67]
	s_setprio 0
	s_barrier
	s_mov_b64 s[56:57], s[34:35]
	ds_read_b128 v[174:177], v143 offset:16384
	ds_read_b128 v[178:181], v143 offset:17408
	ds_read_b128 v[182:185], v143 offset:18432
	ds_read_b128 v[186:189], v143 offset:19456
	ds_read_b128 v[190:193], v143 offset:20480
	ds_read_b128 v[194:197], v143 offset:21504
	ds_read_b128 v[202:205], v143 offset:22528
	ds_read_b128 v[206:209], v143 offset:23552
	s_add_i32 s55, s39, s0
	v_lshl_add_u64 v[138:139], s[56:57], 0, v[130:131]
	s_add_u32 s56, s34, 0x42000
	s_mov_b32 m0, s55
	s_addc_u32 s57, s35, 0
	global_load_lds_dwordx4 v[138:139], off
	s_add_i32 m0, s55, 0x2000
	v_lshl_add_u64 v[138:139], s[56:57], 0, v[130:131]
	s_add_u32 s56, s34, 0x84000
	s_addc_u32 s57, s35, 0
	s_add_i32 s55, s40, s0
	s_add_u32 s34, s34, 0xc6000
	global_load_lds_dwordx4 v[138:139], off
	s_mov_b32 m0, s55
	v_lshl_add_u64 v[138:139], s[56:57], 0, v[130:131]
	s_addc_u32 s35, s35, 0
	global_load_lds_dwordx4 v[138:139], off
	s_add_i32 m0, s55, 0x2000
	v_lshl_add_u64 v[138:139], s[34:35], 0, v[130:131]
	s_mov_b64 s[34:35], s[30:31]
	global_load_lds_dwordx4 v[138:139], off
	s_mov_b32 m0, s1
	v_lshl_add_u64 v[138:139], s[34:35], 0, v[128:129]
	s_add_u32 s34, s30, 0x42000
	s_addc_u32 s35, s31, 0
	global_load_lds_dwordx4 v[138:139], off
	s_mov_b32 m0, s2
	v_lshl_add_u64 v[138:139], s[34:35], 0, v[128:129]
	global_load_lds_dwordx4 v[138:139], off
	s_waitcnt vmcnt(8)
	s_waitcnt lgkmcnt(0)
	s_barrier
; #define G8_STAGE(bufoff, gbase, NM) do { _Pragma("unroll") for (int _i = 0; _i < 2; ++_i) { \
;     const char* _b = (const char*)(gbase) + (_i ? p2##NM : (size_t)0); asm volatile("" : "+s"(_b));     \
;     __builtin_amdgcn_global_load_lds((const unsigned*)(_b + voff##NM), (LAS unsigned*)(lds + (bufoff) + ldsw + _i * 8192), 16, 0, 0); } } while (0)
; #define G8_WAIT_V(n) asm volatile("s_waitcnt vmcnt(" #n ")" ::: "memory")
; #define G8_WAIT_L(n) asm volatile("s_waitcnt lgkmcnt(" #n ")" ::: "memory")
; #define G8_BAR __builtin_amdgcn_s_barrier()
; #define G8_SCHED __builtin_amdgcn_sched_barrier(0)
;     ...
;       G8_WAIT_V(8); G8_WAIT_L(0); G8_BAR; if (d0a) G8_MMA(1, 0, At, B0); if (d1a) G8_MMA(1, 1, At, B1); G8_BAR; G8_SCHED;
;       G8_LDB(B0, 1, 0); G8_LDB(B1, 1, 1); G8_SCHED; G8_LDA(At, 1, 0); G8_STAGE(G8_SA(0, 1), a2 + hstepA, A);
;       G8_WAIT_V(8); G8_WAIT_L(0); G8_BAR; if (d0b) G8_MMA(0, 0, At, B0); if (d1b) G8_MMA(0, 1, At, B1); G8_BAR; G8_SCHED;
;       G8_LDA(At, 1, 1); G8_STAGE(G8_SB(1, 0), b3, B); G8_STAGE(G8_SB(1, 1), b3 + hstepB, B); G8_STAGE(G8_SA(1, 0), a3, A);
	s_setprio 1
	s_waitcnt lgkmcnt(0)
	v_mfma_f32_16x16x32_bf16 v[60:63], v[134:137], v[174:177], v[60:63]
	v_mfma_f32_16x16x32_bf16 v[56:59], v[150:153], v[174:177], v[56:59]
	v_mfma_f32_16x16x32_bf16 v[44:47], v[134:137], v[182:185], v[44:47]
	v_mfma_f32_16x16x32_bf16 v[40:43], v[150:153], v[182:185], v[40:43]
	v_mfma_f32_16x16x32_bf16 v[28:31], v[134:137], v[190:193], v[28:31]
	v_mfma_f32_16x16x32_bf16 v[24:27], v[150:153], v[190:193], v[24:27]
	v_mfma_f32_16x16x32_bf16 v[12:15], v[134:137], v[202:205], v[12:15]
	v_mfma_f32_16x16x32_bf16 v[8:11], v[150:153], v[202:205], v[8:11]
	v_mfma_f32_16x16x32_bf16 v[60:63], v[146:149], v[178:181], v[60:63]
	v_mfma_f32_16x16x32_bf16 v[56:59], v[154:157], v[178:181], v[56:59]
	v_mfma_f32_16x16x32_bf16 v[44:47], v[146:149], v[186:189], v[44:47]
	v_mfma_f32_16x16x32_bf16 v[40:43], v[154:157], v[186:189], v[40:43]
	v_mfma_f32_16x16x32_bf16 v[28:31], v[146:149], v[194:197], v[28:31]
	v_mfma_f32_16x16x32_bf16 v[24:27], v[154:157], v[194:197], v[24:27]
	v_mfma_f32_16x16x32_bf16 v[12:15], v[146:149], v[206:209], v[12:15]
	v_mfma_f32_16x16x32_bf16 v[8:11], v[154:157], v[206:209], v[8:11]
	s_setprio 0
	s_setprio 1
	v_mfma_f32_16x16x32_bf16 v[52:55], v[158:161], v[174:177], v[52:55]
	v_mfma_f32_16x16x32_bf16 v[48:51], v[166:169], v[174:177], v[48:51]
	v_mfma_f32_16x16x32_bf16 v[36:39], v[158:161], v[182:185], v[36:39]
	v_mfma_f32_16x16x32_bf16 v[32:35], v[166:169], v[182:185], v[32:35]
	v_mfma_f32_16x16x32_bf16 v[20:23], v[158:161], v[190:193], v[20:23]
	v_mfma_f32_16x16x32_bf16 v[16:19], v[166:169], v[190:193], v[16:19]
	v_mfma_f32_16x16x32_bf16 v[4:7], v[158:161], v[202:205], v[4:7]
	v_mfma_f32_16x16x32_bf16 v[0:3], v[166:169], v[202:205], v[0:3]
	v_mfma_f32_16x16x32_bf16 v[52:55], v[162:165], v[178:181], v[52:55]
	v_mfma_f32_16x16x32_bf16 v[48:51], v[170:173], v[178:181], v[48:51]
	v_mfma_f32_16x16x32_bf16 v[36:39], v[162:165], v[186:189], v[36:39]
	v_mfma_f32_16x16x32_bf16 v[32:35], v[170:173], v[186:189], v[32:35]
	v_mfma_f32_16x16x32_bf16 v[20:23], v[162:165], v[194:197], v[20:23]
	v_mfma_f32_16x16x32_bf16 v[16:19], v[170:173], v[194:197], v[16:19]
	v_mfma_f32_16x16x32_bf16 v[4:7], v[162:165], v[206:209], v[4:7]
	v_mfma_f32_16x16x32_bf16 v[0:3], v[170:173], v[206:209], v[0:3]
	s_setprio 0
	s_barrier
	s_add_i32 s55, 0, 0x18000
	v_add_u32_e32 v132, s55, v140
	s_add_i32 s56, 0, 0x1c000
	ds_read_b128 v[134:137], v132
	ds_read_b128 v[146:149], v132 offset:1024
	ds_read_b128 v[150:153], v132 offset:2048
	ds_read_b128 v[154:157], v132 offset:3072
	v_add_u32_e32 v132, 0x1000, v132
	ds_read_b128 v[158:161], v132
	ds_read_b128 v[162:165], v132 offset:1024
	ds_read_b128 v[166:169], v132 offset:2048
	ds_read_b128 v[170:173], v132 offset:3072
	s_add_u32 s34, s30, 0x84000
	s_addc_u32 s35, s31, 0
	s_add_u32 s30, s30, 0xc6000
	s_mov_b32 m0, s3
	ds_read_b128 v[174:177], v143 offset:32768
	ds_read_b128 v[178:181], v143 offset:33792
	ds_read_b128 v[182:185], v143 offset:34816
	ds_read_b128 v[186:189], v143 offset:35840
	ds_read_b128 v[190:193], v143 offset:36864
	ds_read_b128 v[194:197], v143 offset:37888
	ds_read_b128 v[202:205], v143 offset:38912
	ds_read_b128 v[206:209], v143 offset:39936
	s_addc_u32 s31, s31, 0
	v_lshl_add_u64 v[138:139], s[34:35], 0, v[128:129]
	global_load_lds_dwordx4 v[138:139], off
	s_mov_b32 m0, s33
	v_lshl_add_u64 v[138:139], s[30:31], 0, v[128:129]
	global_load_lds_dwordx4 v[138:139], off
	s_waitcnt vmcnt(8)
	s_waitcnt lgkmcnt(0)
	s_barrier
	s_setprio 1
	s_waitcnt lgkmcnt(0)
	v_mfma_f32_16x16x32_bf16 v[124:127], v[134:137], v[174:177], v[124:127]
	v_mfma_f32_16x16x32_bf16 v[120:123], v[150:153], v[174:177], v[120:123]
	v_mfma_f32_16x16x32_bf16 v[108:111], v[134:137], v[182:185], v[108:111]
	v_mfma_f32_16x16x32_bf16 v[104:107], v[150:153], v[182:185], v[104:107]
	v_mfma_f32_16x16x32_bf16 v[92:95], v[134:137], v[190:193], v[92:95]
	v_mfma_f32_16x16x32_bf16 v[88:91], v[150:153], v[190:193], v[88:91]
	v_mfma_f32_16x16x32_bf16 v[76:79], v[134:137], v[202:205], v[76:79]
	v_mfma_f32_16x16x32_bf16 v[72:75], v[150:153], v[202:205], v[72:75]
	v_mfma_f32_16x16x32_bf16 v[124:127], v[146:149], v[178:181], v[124:127]
	v_mfma_f32_16x16x32_bf16 v[120:123], v[154:157], v[178:181], v[120:123]
	v_mfma_f32_16x16x32_bf16 v[108:111], v[146:149], v[186:189], v[108:111]
	v_mfma_f32_16x16x32_bf16 v[104:107], v[154:157], v[186:189], v[104:107]
	v_mfma_f32_16x16x32_bf16 v[92:95], v[146:149], v[194:197], v[92:95]
	v_mfma_f32_16x16x32_bf16 v[88:91], v[154:157], v[194:197], v[88:91]
	v_mfma_f32_16x16x32_bf16 v[76:79], v[146:149], v[206:209], v[76:79]
	v_mfma_f32_16x16x32_bf16 v[72:75], v[154:157], v[206:209], v[72:75]
	s_setprio 0
	s_setprio 1
	v_mfma_f32_16x16x32_bf16 v[116:119], v[158:161], v[174:177], v[116:119]
	v_mfma_f32_16x16x32_bf16 v[112:115], v[166:169], v[174:177], v[112:115]
	v_mfma_f32_16x16x32_bf16 v[100:103], v[158:161], v[182:185], v[100:103]
	v_mfma_f32_16x16x32_bf16 v[96:99], v[166:169], v[182:185], v[96:99]
	v_mfma_f32_16x16x32_bf16 v[84:87], v[158:161], v[190:193], v[84:87]
	v_mfma_f32_16x16x32_bf16 v[80:83], v[166:169], v[190:193], v[80:83]
	v_mfma_f32_16x16x32_bf16 v[68:71], v[158:161], v[202:205], v[68:71]
	v_mfma_f32_16x16x32_bf16 v[64:67], v[166:169], v[202:205], v[64:67]
	v_mfma_f32_16x16x32_bf16 v[116:119], v[162:165], v[178:181], v[116:119]
	v_mfma_f32_16x16x32_bf16 v[112:115], v[170:173], v[178:181], v[112:115]
	v_mfma_f32_16x16x32_bf16 v[100:103], v[162:165], v[186:189], v[100:103]
	v_mfma_f32_16x16x32_bf16 v[96:99], v[170:173], v[186:189], v[96:99]
	v_mfma_f32_16x16x32_bf16 v[84:87], v[162:165], v[194:197], v[84:87]
	v_mfma_f32_16x16x32_bf16 v[80:83], v[170:173], v[194:197], v[80:83]
	v_mfma_f32_16x16x32_bf16 v[68:71], v[162:165], v[206:209], v[68:71]
	v_mfma_f32_16x16x32_bf16 v[64:67], v[170:173], v[206:209], v[64:67]
	s_setprio 0
	s_barrier
; #define G8_STAGE(bufoff, gbase, NM) do { _Pragma("unroll") for (int _i = 0; _i < 2; ++_i) { \
;     const char* _b = (const char*)(gbase) + (_i ? p2##NM : (size_t)0); asm volatile("" : "+s"(_b));     \
;     __builtin_amdgcn_global_load_lds((const unsigned*)(_b + voff##NM), (LAS unsigned*)(lds + (bufoff) + ldsw + _i * 8192), 16, 0, 0); } } while (0)
; #define G8_WAIT_V(n) asm volatile("s_waitcnt vmcnt(" #n ")" ::: "memory")
; #define G8_WAIT_L(n) asm volatile("s_waitcnt lgkmcnt(" #n ")" ::: "memory")
; #define G8_BAR __builtin_amdgcn_s_barrier()
; #define G8_SCHED __builtin_amdgcn_sched_barrier(0)
;     ...
;       G8_WAIT_V(8); G8_WAIT_L(0); G8_BAR; if (d0b) G8_MMA(0, 0, At, B0); if (d1b) G8_MMA(0, 1, At, B1); G8_BAR; G8_SCHED;
;       G8_LDA(At, 1, 1); G8_STAGE(G8_SB(1, 0), b3, B); G8_STAGE(G8_SB(1, 1), b3 + hstepB, B); G8_STAGE(G8_SA(1, 0), a3, A);
;       G8_WAIT_V(8); G8_WAIT_L(0); G8_BAR; if (d0b) G8_MMA(1, 0, At, B0); if (d1b) G8_MMA(1, 1, At, B1); G8_BAR; G8_SCHED;
;     }
;     if (wr == 0) G8_BAR;
;     {
;       int t2 = threadIdx.x; asm volatile("" : "+v"(t2));
;       const int w2 = __builtin_amdgcn_readfirstlane(t2 >> 6), l2 = t2 & 63;
;       E(acc, cur, w2 >> 2, w2 & 3, l2 & 15, l2 >> 4); }
;   __device__ __forceinline__ void operator()(const Acc& acc, const GUnit& u, int wr, int wc, int fr, int fq) const {
;     const int row0 = u.pm * 256 + wr * 64 + fr;
;     bf16_t* ob = (u.pn < nsplit ? O0 + (size_t)u.pn * 256 : O1 + (size_t)(u.pn - nsplit) * 256) + wc * 32 + 8 * fq;
; #pragma unroll
;     for (int ai = 0; ai < 2; ++ai)
; #pragma unroll
;       for (int m = 0; m < 4; ++m) {
;         const int row = row0 + ai * 128 + m * 16;
	s_mov_b64 s[30:31], s[28:29]
	ds_read_b128 v[174:177], v143 offset:49152
	ds_read_b128 v[178:181], v143 offset:50176
	ds_read_b128 v[182:185], v143 offset:51200
	ds_read_b128 v[186:189], v143 offset:52224
	ds_read_b128 v[190:193], v143 offset:53248
	ds_read_b128 v[194:197], v143 offset:54272
	ds_read_b128 v[202:205], v143 offset:55296
	ds_read_b128 v[206:209], v143 offset:56320
	s_add_i32 s34, s55, s0
	v_lshl_add_u64 v[138:139], s[30:31], 0, v[130:131]
	s_add_u32 s30, s28, 0x42000
	s_mov_b32 m0, s34
	s_addc_u32 s31, s29, 0
	global_load_lds_dwordx4 v[138:139], off
	s_add_i32 m0, s34, 0x2000
	v_lshl_add_u64 v[138:139], s[30:31], 0, v[130:131]
	s_add_u32 s30, s28, 0x84000
	s_addc_u32 s31, s29, 0
	global_load_lds_dwordx4 v[138:139], off
	s_nop 0
	v_lshl_add_u64 v[138:139], s[30:31], 0, v[130:131]
	s_add_i32 s30, s56, s0
	s_add_u32 s28, s28, 0xc6000
	s_mov_b32 m0, s30
	s_addc_u32 s29, s29, 0
	global_load_lds_dwordx4 v[138:139], off
	s_add_i32 m0, s30, 0x2000
	v_lshl_add_u64 v[138:139], s[28:29], 0, v[130:131]
	s_mov_b64 s[28:29], s[26:27]
	s_add_u32 s26, s26, 0x42000
	global_load_lds_dwordx4 v[138:139], off
	s_mov_b32 m0, s37
	v_lshl_add_u64 v[138:139], s[28:29], 0, v[128:129]
	s_addc_u32 s27, s27, 0
	global_load_lds_dwordx4 v[138:139], off
	s_mov_b32 m0, s38
	v_lshl_add_u64 v[138:139], s[26:27], 0, v[128:129]
	global_load_lds_dwordx4 v[138:139], off
	s_waitcnt vmcnt(8)
	s_waitcnt lgkmcnt(0)
	s_barrier
	s_setprio 1
	s_waitcnt lgkmcnt(0)
	v_mfma_f32_16x16x32_bf16 v[60:63], v[134:137], v[174:177], v[60:63]
	v_mfma_f32_16x16x32_bf16 v[56:59], v[150:153], v[174:177], v[56:59]
	v_mfma_f32_16x16x32_bf16 v[44:47], v[134:137], v[182:185], v[44:47]
	v_mfma_f32_16x16x32_bf16 v[40:43], v[150:153], v[182:185], v[40:43]
	v_mfma_f32_16x16x32_bf16 v[28:31], v[134:137], v[190:193], v[28:31]
	v_mfma_f32_16x16x32_bf16 v[24:27], v[150:153], v[190:193], v[24:27]
	v_mfma_f32_16x16x32_bf16 v[12:15], v[134:137], v[202:205], v[12:15]
	v_mfma_f32_16x16x32_bf16 v[8:11], v[150:153], v[202:205], v[8:11]
	v_mfma_f32_16x16x32_bf16 v[60:63], v[146:149], v[178:181], v[60:63]
	v_mfma_f32_16x16x32_bf16 v[56:59], v[154:157], v[178:181], v[56:59]
	v_mfma_f32_16x16x32_bf16 v[44:47], v[146:149], v[186:189], v[44:47]
	v_mfma_f32_16x16x32_bf16 v[40:43], v[154:157], v[186:189], v[40:43]
	v_mfma_f32_16x16x32_bf16 v[28:31], v[146:149], v[194:197], v[28:31]
	v_mfma_f32_16x16x32_bf16 v[24:27], v[154:157], v[194:197], v[24:27]
	v_mfma_f32_16x16x32_bf16 v[12:15], v[146:149], v[206:209], v[12:15]
	v_mfma_f32_16x16x32_bf16 v[8:11], v[154:157], v[206:209], v[8:11]
	s_setprio 0
	s_setprio 1
	v_mfma_f32_16x16x32_bf16 v[52:55], v[158:161], v[174:177], v[52:55]
	v_mfma_f32_16x16x32_bf16 v[48:51], v[166:169], v[174:177], v[48:51]
	v_mfma_f32_16x16x32_bf16 v[36:39], v[158:161], v[182:185], v[36:39]
	v_mfma_f32_16x16x32_bf16 v[32:35], v[166:169], v[182:185], v[32:35]
	v_mfma_f32_16x16x32_bf16 v[20:23], v[158:161], v[190:193], v[20:23]
	v_mfma_f32_16x16x32_bf16 v[16:19], v[166:169], v[190:193], v[16:19]
	v_mfma_f32_16x16x32_bf16 v[4:7], v[158:161], v[202:205], v[4:7]
	v_mfma_f32_16x16x32_bf16 v[0:3], v[166:169], v[202:205], v[0:3]
	v_mfma_f32_16x16x32_bf16 v[52:55], v[162:165], v[178:181], v[52:55]
	v_mfma_f32_16x16x32_bf16 v[48:51], v[170:173], v[178:181], v[48:51]
	v_mfma_f32_16x16x32_bf16 v[36:39], v[162:165], v[186:189], v[36:39]
	v_mfma_f32_16x16x32_bf16 v[32:35], v[170:173], v[186:189], v[32:35]
	v_mfma_f32_16x16x32_bf16 v[20:23], v[162:165], v[194:197], v[20:23]
	v_mfma_f32_16x16x32_bf16 v[16:19], v[170:173], v[194:197], v[16:19]
	v_mfma_f32_16x16x32_bf16 v[4:7], v[162:165], v[206:209], v[4:7]
	v_mfma_f32_16x16x32_bf16 v[0:3], v[170:173], v[206:209], v[0:3]
	s_setprio 0
	s_barrier
	s_add_i32 s54, s54, 2
	s_add_u32 s50, s50, 0x100
	s_addc_u32 s51, s51, 0
	s_add_u32 s52, s52, 0x100
	s_addc_u32 s53, s53, 0
	s_add_u32 s4, s4, 0x100
	s_addc_u32 s5, s5, 0
	s_cmp_gt_u32 s54, 29
	s_cbranch_scc0 .LBB0_1125
	s_and_b64 vcc, exec, s[12:13]
	s_cbranch_vccz .LBB0_1128
	s_barrier
.LBB0_1128:
	v_mov_b32_e32 v132, v200
	s_lshl_b32 s4, s48, 8
	s_mov_b64 s[62:63], 0x10000
	v_readfirstlane_b32 s26, v132
	s_ashr_i32 s5, s26, 2
	s_andn2_b32 s5, s5, 63
	s_add_i32 s5, s5, s4
	v_and_or_b32 v138, v132, 15, s5
	v_ashrrev_i32_e32 v139, 31, v138
	v_lshl_add_u64 v[134:135], v[138:139], 2, s[8:9]
	global_load_dword v145, v[134:135], off
	v_readlane_b32 s28, v254, 16
	s_add_i32 s4, s49, -16
	s_ashr_i32 s5, s49, 31
	v_readlane_b32 s29, v254, 17
	s_cmp_lt_i32 s49, 16
	v_readlane_b32 s28, v254, 38
	v_lshlrev_b64 v[136:137], 13, v[138:139]
	s_cselect_b32 s5, s5, 0
	s_cselect_b32 s4, s49, s4
	v_readlane_b32 s30, v254, 18
	v_readlane_b32 s31, v254, 19
	v_readlane_b32 s29, v254, 39
	s_cselect_b32 s27, s31, s29
	s_cselect_b32 s28, s30, s28
	s_lshl_b64 s[4:5], s[4:5], 9
	s_add_u32 s4, s28, s4
	s_addc_u32 s5, s27, s5
	s_and_b32 s26, s26, 0xc0
	s_lshl_b32 s26, s26, 1
	s_add_u32 s4, s4, s26
	v_and_b32_e32 v198, 8, v132
	v_xor_b32_e32 v199, 8, v198
	v_lshlrev_b32_e32 v199, 13, v199
	v_lshl_or_b32 v199, v198, 3, v199
	v_and_or_b32 v132, v132, 48, v199
	s_addc_u32 s5, s5, 0
	s_sub_u32 s4, s4, 0x10000
	s_subb_u32 s5, s5, 0
	v_lshl_add_u64 v[150:151], s[4:5], 0, v[132:133]
	v_or_b32_e32 v146, 16, v138
	v_ashrrev_i32_e32 v147, 31, v146
	v_lshl_add_u64 v[136:137], v[150:151], 0, v[136:137]
	v_lshl_add_u64 v[148:149], v[146:147], 2, s[8:9]
	s_waitcnt vmcnt(0)
; __device__ __forceinline__ u32x4 pack8(f32x4 a, f32x4 b) { u32x4 w; w[0] = cvt_pk_bf16(a[0], a[1]); w[1] = cvt_pk_bf16(a[2], a[3]); w[2] = cvt_pk_bf16(b[0], b[1]); w[3] = cvt_pk_bf16(b[2], b[3]); return w; }
;   __device__ __forceinline__ void operator()(const Acc& acc, const GUnit& u, int wr, int wc, int fr, int fq) const {
;     ...
;     for (int ai = 0; ai < 2; ++ai)
; #pragma unroll
;       for (int m = 0; m < 4; ++m) {
;         const int row = row0 + ai * 128 + m * 16;
;         const float rs = ss ? rsqrtf(ss[row] * (1.f / 2048.f) + EPS) : 1.f;
; #pragma unroll
;         for (int bj = 0; bj < 2; ++bj) *(u32x4*)(ob + (size_t)row * ld + bj * 128) = pack8(acc[ai][bj][m][0] * rs, acc[ai][bj][m][1] * rs);
	v_fmamk_f32 v139, v145, 0x3a000000, v144
	v_mul_f32_e32 v145, 0x4b800000, v139
	v_cmp_gt_f32_e32 vcc, s41, v139
	s_nop 1
	v_cndmask_b32_e32 v139, v139, v145, vcc
	v_rsq_f32_e32 v139, v139
	s_nop 0
	v_mul_f32_e32 v132, 0x45800000, v139
	v_cndmask_b32_e32 v132, v139, v132, vcc
	v_pk_mul_f32 v[126:127], v[126:127], v[132:133] op_sel_hi:[1,0]
	v_pk_mul_f32 v[124:125], v[124:125], v[132:133] op_sel_hi:[1,0]
	v_pk_mul_f32 v[122:123], v[122:123], v[132:133] op_sel_hi:[1,0]
	v_pk_mul_f32 v[120:121], v[120:121], v[132:133] op_sel_hi:[1,0]
	v_pk_mul_f32 v[118:119], v[118:119], v[132:133] op_sel_hi:[1,0]
	v_pk_mul_f32 v[116:117], v[116:117], v[132:133] op_sel_hi:[1,0]
	v_pk_mul_f32 v[152:153], v[114:115], v[132:133] op_sel_hi:[1,0]
	v_pk_mul_f32 v[154:155], v[112:113], v[132:133] op_sel_hi:[1,0]
	v_cvt_pk_bf16_f32 v112, v124, v125
	v_cvt_pk_bf16_f32 v113, v126, v127
	v_cvt_pk_bf16_f32 v114, v120, v121
	v_cvt_pk_bf16_f32 v115, v122, v123
	v_cvt_pk_bf16_f32 v116, v116, v117
	v_cvt_pk_bf16_f32 v117, v118, v119
	s_nop 0
	v_cvt_pk_bf16_f32 v118, v154, v155
	v_cvt_pk_bf16_f32 v119, v152, v153
	v_mov_b32_e32 v220, v112
	v_mov_b32_e32 v221, v113
	v_mov_b32_e32 v222, v114
	v_mov_b32_e32 v223, v115
	v_mov_b32_dpp v112, v116 row_ror:8 row_mask:0xf bank_mask:0xc
	v_mov_b32_dpp v113, v117 row_ror:8 row_mask:0xf bank_mask:0xc
	v_mov_b32_dpp v114, v118 row_ror:8 row_mask:0xf bank_mask:0xc
	v_mov_b32_dpp v115, v119 row_ror:8 row_mask:0xf bank_mask:0xc
	v_mov_b32_dpp v116, v220 row_ror:8 row_mask:0xf bank_mask:0x3
	v_mov_b32_dpp v117, v221 row_ror:8 row_mask:0xf bank_mask:0x3
	v_mov_b32_dpp v118, v222 row_ror:8 row_mask:0xf bank_mask:0x3
	v_mov_b32_dpp v119, v223 row_ror:8 row_mask:0xf bank_mask:0x3
	v_lshl_add_u64 v[224:225], v[136:137], 0, s[62:63]
	global_store_dwordx4 v[136:137], v[112:115], off
	global_store_dwordx4 v[224:225], v[116:119], off
	global_load_dword v114, v[148:149], off
	v_or_b32_e32 v112, 32, v138
	v_ashrrev_i32_e32 v113, 31, v112
	v_lshl_add_u64 v[116:117], v[112:113], 2, s[8:9]
	s_waitcnt vmcnt(0)
	v_fmamk_f32 v114, v114, 0x3a000000, v144
	v_mul_f32_e32 v115, 0x4b800000, v114
	v_cmp_gt_f32_e32 vcc, s41, v114
	s_nop 1
	v_cndmask_b32_e32 v114, v114, v115, vcc
	v_rsq_f32_e32 v118, v114
	v_lshlrev_b64 v[114:115], 13, v[146:147]
	v_lshl_add_u64 v[114:115], v[150:151], 0, v[114:115]
	v_mul_f32_e32 v119, 0x45800000, v118
	v_cndmask_b32_e32 v118, v118, v119, vcc
	v_pk_mul_f32 v[110:111], v[110:111], v[118:119] op_sel_hi:[1,0]
	v_pk_mul_f32 v[108:109], v[108:109], v[118:119] op_sel_hi:[1,0]
	v_pk_mul_f32 v[106:107], v[106:107], v[118:119] op_sel_hi:[1,0]
	v_pk_mul_f32 v[104:105], v[104:105], v[118:119] op_sel_hi:[1,0]
	v_pk_mul_f32 v[102:103], v[102:103], v[118:119] op_sel_hi:[1,0]
	v_pk_mul_f32 v[100:101], v[100:101], v[118:119] op_sel_hi:[1,0]
	v_pk_mul_f32 v[120:121], v[98:99], v[118:119] op_sel_hi:[1,0]
	v_pk_mul_f32 v[118:119], v[96:97], v[118:119] op_sel_hi:[1,0]
	v_cvt_pk_bf16_f32 v96, v108, v109
	v_cvt_pk_bf16_f32 v97, v110, v111
	v_cvt_pk_bf16_f32 v98, v104, v105
	v_cvt_pk_bf16_f32 v99, v106, v107
	v_cvt_pk_bf16_f32 v100, v100, v101
	v_cvt_pk_bf16_f32 v101, v102, v103
	s_nop 0
	v_cvt_pk_bf16_f32 v102, v118, v119
	v_cvt_pk_bf16_f32 v103, v120, v121
	v_mov_b32_e32 v220, v96
	v_mov_b32_e32 v221, v97
	v_mov_b32_e32 v222, v98
	v_mov_b32_e32 v223, v99
	v_mov_b32_dpp v96, v100 row_ror:8 row_mask:0xf bank_mask:0xc
	v_mov_b32_dpp v97, v101 row_ror:8 row_mask:0xf bank_mask:0xc
	v_mov_b32_dpp v98, v102 row_ror:8 row_mask:0xf bank_mask:0xc
	v_mov_b32_dpp v99, v103 row_ror:8 row_mask:0xf bank_mask:0xc
	v_mov_b32_dpp v100, v220 row_ror:8 row_mask:0xf bank_mask:0x3
	v_mov_b32_dpp v101, v221 row_ror:8 row_mask:0xf bank_mask:0x3
	v_mov_b32_dpp v102, v222 row_ror:8 row_mask:0xf bank_mask:0x3
	v_mov_b32_dpp v103, v223 row_ror:8 row_mask:0xf bank_mask:0x3
	v_lshl_add_u64 v[224:225], v[114:115], 0, s[62:63]
	global_store_dwordx4 v[114:115], v[96:99], off
	global_store_dwordx4 v[224:225], v[100:103], off
	global_load_dword v98, v[116:117], off
	v_or_b32_e32 v96, 48, v138
	v_ashrrev_i32_e32 v97, 31, v96
	v_lshl_add_u64 v[100:101], v[96:97], 2, s[8:9]
	s_waitcnt vmcnt(0)
	v_fmamk_f32 v98, v98, 0x3a000000, v144
	v_mul_f32_e32 v99, 0x4b800000, v98
	v_cmp_gt_f32_e32 vcc, s41, v98
	s_nop 1
	v_cndmask_b32_e32 v98, v98, v99, vcc
	v_rsq_f32_e32 v102, v98
	v_lshlrev_b64 v[98:99], 13, v[112:113]
	v_lshl_add_u64 v[98:99], v[150:151], 0, v[98:99]
	v_mul_f32_e32 v103, 0x45800000, v102
	v_cndmask_b32_e32 v102, v102, v103, vcc
	v_pk_mul_f32 v[94:95], v[94:95], v[102:103] op_sel_hi:[1,0]
	v_pk_mul_f32 v[92:93], v[92:93], v[102:103] op_sel_hi:[1,0]
	v_pk_mul_f32 v[90:91], v[90:91], v[102:103] op_sel_hi:[1,0]
	v_pk_mul_f32 v[88:89], v[88:89], v[102:103] op_sel_hi:[1,0]
	v_pk_mul_f32 v[86:87], v[86:87], v[102:103] op_sel_hi:[1,0]
	v_pk_mul_f32 v[84:85], v[84:85], v[102:103] op_sel_hi:[1,0]
	v_pk_mul_f32 v[104:105], v[82:83], v[102:103] op_sel_hi:[1,0]
	v_pk_mul_f32 v[102:103], v[80:81], v[102:103] op_sel_hi:[1,0]
	v_cvt_pk_bf16_f32 v80, v92, v93
	v_cvt_pk_bf16_f32 v81, v94, v95
	v_cvt_pk_bf16_f32 v82, v88, v89
	v_cvt_pk_bf16_f32 v83, v90, v91
	v_cvt_pk_bf16_f32 v84, v84, v85
	v_cvt_pk_bf16_f32 v85, v86, v87
	s_nop 0
	v_cvt_pk_bf16_f32 v86, v102, v103
	v_cvt_pk_bf16_f32 v87, v104, v105
	v_mov_b32_e32 v220, v80
	v_mov_b32_e32 v221, v81
	v_mov_b32_e32 v222, v82
	v_mov_b32_e32 v223, v83
	v_mov_b32_dpp v80, v84 row_ror:8 row_mask:0xf bank_mask:0xc
	v_mov_b32_dpp v81, v85 row_ror:8 row_mask:0xf bank_mask:0xc
	v_mov_b32_dpp v82, v86 row_ror:8 row_mask:0xf bank_mask:0xc
	v_mov_b32_dpp v83, v87 row_ror:8 row_mask:0xf bank_mask:0xc
	v_mov_b32_dpp v84, v220 row_ror:8 row_mask:0xf bank_mask:0x3
	v_mov_b32_dpp v85, v221 row_ror:8 row_mask:0xf bank_mask:0x3
	v_mov_b32_dpp v86, v222 row_ror:8 row_mask:0xf bank_mask:0x3
	v_mov_b32_dpp v87, v223 row_ror:8 row_mask:0xf bank_mask:0x3
	v_lshl_add_u64 v[224:225], v[98:99], 0, s[62:63]
	global_store_dwordx4 v[98:99], v[80:83], off
	global_store_dwordx4 v[224:225], v[84:87], off
	global_load_dword v80, v[100:101], off
	s_waitcnt vmcnt(0)
; __device__ __forceinline__ u32x4 pack8(f32x4 a, f32x4 b) { u32x4 w; w[0] = cvt_pk_bf16(a[0], a[1]); w[1] = cvt_pk_bf16(a[2], a[3]); w[2] = cvt_pk_bf16(b[0], b[1]); w[3] = cvt_pk_bf16(b[2], b[3]); return w; }
;   __device__ __forceinline__ void operator()(const Acc& acc, const GUnit& u, int wr, int wc, int fr, int fq) const {
;     ...
;     for (int ai = 0; ai < 2; ++ai)
; #pragma unroll
;       for (int m = 0; m < 4; ++m) {
;         const int row = row0 + ai * 128 + m * 16;
;         const float rs = ss ? rsqrtf(ss[row] * (1.f / 2048.f) + EPS) : 1.f;
; #pragma unroll
;         for (int bj = 0; bj < 2; ++bj) *(u32x4*)(ob + (size_t)row * ld + bj * 128) = pack8(acc[ai][bj][m][0] * rs, acc[ai][bj][m][1] * rs);
	v_fmamk_f32 v80, v80, 0x3a000000, v144
	v_mul_f32_e32 v81, 0x4b800000, v80
	v_cmp_gt_f32_e32 vcc, s41, v80
	s_nop 1
	v_cndmask_b32_e32 v80, v80, v81, vcc
	v_rsq_f32_e32 v82, v80
	v_lshlrev_b64 v[80:81], 13, v[96:97]
	v_lshl_add_u64 v[80:81], v[150:151], 0, v[80:81]
	v_mul_f32_e32 v83, 0x45800000, v82
	v_cndmask_b32_e32 v82, v82, v83, vcc
	v_pk_mul_f32 v[78:79], v[78:79], v[82:83] op_sel_hi:[1,0]
	v_pk_mul_f32 v[76:77], v[76:77], v[82:83] op_sel_hi:[1,0]
	v_pk_mul_f32 v[74:75], v[74:75], v[82:83] op_sel_hi:[1,0]
	v_pk_mul_f32 v[72:73], v[72:73], v[82:83] op_sel_hi:[1,0]
	v_pk_mul_f32 v[70:71], v[70:71], v[82:83] op_sel_hi:[1,0]
	v_pk_mul_f32 v[68:69], v[68:69], v[82:83] op_sel_hi:[1,0]
	v_pk_mul_f32 v[84:85], v[66:67], v[82:83] op_sel_hi:[1,0]
	v_pk_mul_f32 v[82:83], v[64:65], v[82:83] op_sel_hi:[1,0]
	v_cvt_pk_bf16_f32 v64, v76, v77
	v_cvt_pk_bf16_f32 v65, v78, v79
	v_cvt_pk_bf16_f32 v66, v72, v73
	v_cvt_pk_bf16_f32 v67, v74, v75
	v_cvt_pk_bf16_f32 v68, v68, v69
	v_cvt_pk_bf16_f32 v69, v70, v71
	s_nop 0
	v_cvt_pk_bf16_f32 v70, v82, v83
	v_cvt_pk_bf16_f32 v71, v84, v85
	v_mov_b32_e32 v220, v64
	v_mov_b32_e32 v221, v65
	v_mov_b32_e32 v222, v66
	v_mov_b32_e32 v223, v67
	v_mov_b32_dpp v64, v68 row_ror:8 row_mask:0xf bank_mask:0xc
	v_mov_b32_dpp v65, v69 row_ror:8 row_mask:0xf bank_mask:0xc
	v_mov_b32_dpp v66, v70 row_ror:8 row_mask:0xf bank_mask:0xc
	v_mov_b32_dpp v67, v71 row_ror:8 row_mask:0xf bank_mask:0xc
	v_mov_b32_dpp v68, v220 row_ror:8 row_mask:0xf bank_mask:0x3
	v_mov_b32_dpp v69, v221 row_ror:8 row_mask:0xf bank_mask:0x3
	v_mov_b32_dpp v70, v222 row_ror:8 row_mask:0xf bank_mask:0x3
	v_mov_b32_dpp v71, v223 row_ror:8 row_mask:0xf bank_mask:0x3
	v_lshl_add_u64 v[224:225], v[80:81], 0, s[62:63]
	global_store_dwordx4 v[80:81], v[64:67], off
	global_store_dwordx4 v[224:225], v[68:71], off
	global_load_dword v66, v[134:135], off offset:512
	v_lshl_add_u64 v[64:65], v[136:137], 0, s[14:15]
	s_waitcnt vmcnt(0)
	v_fmamk_f32 v66, v66, 0x3a000000, v144
	v_mul_f32_e32 v67, 0x4b800000, v66
	v_cmp_gt_f32_e32 vcc, s41, v66
	s_nop 1
	v_cndmask_b32_e32 v66, v66, v67, vcc
	v_rsq_f32_e32 v68, v66
	v_add_co_u32_e64 v66, s[4:5], s42, v136
	v_mul_f32_e32 v69, 0x45800000, v68
	v_cndmask_b32_e32 v68, v68, v69, vcc
	v_addc_co_u32_e64 v67, s[4:5], 0, v137, s[4:5]
	v_pk_mul_f32 v[62:63], v[62:63], v[68:69] op_sel_hi:[1,0]
	v_pk_mul_f32 v[60:61], v[60:61], v[68:69] op_sel_hi:[1,0]
	v_pk_mul_f32 v[58:59], v[58:59], v[68:69] op_sel_hi:[1,0]
	v_pk_mul_f32 v[56:57], v[56:57], v[68:69] op_sel_hi:[1,0]
	v_pk_mul_f32 v[54:55], v[54:55], v[68:69] op_sel_hi:[1,0]
	v_pk_mul_f32 v[52:53], v[52:53], v[68:69] op_sel_hi:[1,0]
	v_pk_mul_f32 v[70:71], v[50:51], v[68:69] op_sel_hi:[1,0]
	v_pk_mul_f32 v[68:69], v[48:49], v[68:69] op_sel_hi:[1,0]
	v_cvt_pk_bf16_f32 v48, v60, v61
	v_cvt_pk_bf16_f32 v49, v62, v63
	v_cvt_pk_bf16_f32 v50, v56, v57
	v_cvt_pk_bf16_f32 v51, v58, v59
	v_cvt_pk_bf16_f32 v52, v52, v53
	v_cvt_pk_bf16_f32 v53, v54, v55
	s_nop 0
	v_cvt_pk_bf16_f32 v54, v68, v69
	v_cvt_pk_bf16_f32 v55, v70, v71
	v_mov_b32_e32 v220, v48
	v_mov_b32_e32 v221, v49
	v_mov_b32_e32 v222, v50
	v_mov_b32_e32 v223, v51
	v_mov_b32_dpp v48, v52 row_ror:8 row_mask:0xf bank_mask:0xc
	v_mov_b32_dpp v49, v53 row_ror:8 row_mask:0xf bank_mask:0xc
	v_mov_b32_dpp v50, v54 row_ror:8 row_mask:0xf bank_mask:0xc
	v_mov_b32_dpp v51, v55 row_ror:8 row_mask:0xf bank_mask:0xc
	v_mov_b32_dpp v52, v220 row_ror:8 row_mask:0xf bank_mask:0x3
	v_mov_b32_dpp v53, v221 row_ror:8 row_mask:0xf bank_mask:0x3
	v_mov_b32_dpp v54, v222 row_ror:8 row_mask:0xf bank_mask:0x3
	v_mov_b32_dpp v55, v223 row_ror:8 row_mask:0xf bank_mask:0x3
	v_lshl_add_u64 v[224:225], v[66:67], 0, s[62:63]
	global_store_dwordx4 v[66:67], v[48:51], off
	global_store_dwordx4 v[224:225], v[52:55], off
	global_load_dword v50, v[134:135], off offset:576
	v_lshl_add_u64 v[48:49], v[136:137], 0, s[16:17]
	s_waitcnt vmcnt(0)
	v_fmamk_f32 v50, v50, 0x3a000000, v144
	v_mul_f32_e32 v51, 0x4b800000, v50
	v_cmp_gt_f32_e32 vcc, s41, v50
	s_nop 1
	v_cndmask_b32_e32 v50, v50, v51, vcc
	v_rsq_f32_e32 v52, v50
	v_add_co_u32_e64 v50, s[4:5], s43, v136
	v_mul_f32_e32 v53, 0x45800000, v52
	v_cndmask_b32_e32 v52, v52, v53, vcc
	v_addc_co_u32_e64 v51, s[4:5], 0, v137, s[4:5]
	v_pk_mul_f32 v[46:47], v[46:47], v[52:53] op_sel_hi:[1,0]
	v_pk_mul_f32 v[44:45], v[44:45], v[52:53] op_sel_hi:[1,0]
	v_pk_mul_f32 v[42:43], v[42:43], v[52:53] op_sel_hi:[1,0]
	v_pk_mul_f32 v[40:41], v[40:41], v[52:53] op_sel_hi:[1,0]
	v_pk_mul_f32 v[38:39], v[38:39], v[52:53] op_sel_hi:[1,0]
	v_pk_mul_f32 v[36:37], v[36:37], v[52:53] op_sel_hi:[1,0]
	v_pk_mul_f32 v[54:55], v[34:35], v[52:53] op_sel_hi:[1,0]
	v_pk_mul_f32 v[52:53], v[32:33], v[52:53] op_sel_hi:[1,0]
	v_cvt_pk_bf16_f32 v32, v44, v45
	v_cvt_pk_bf16_f32 v33, v46, v47
	v_cvt_pk_bf16_f32 v34, v40, v41
	v_cvt_pk_bf16_f32 v35, v42, v43
	v_cvt_pk_bf16_f32 v36, v36, v37
	v_cvt_pk_bf16_f32 v37, v38, v39
	s_nop 0
	v_cvt_pk_bf16_f32 v38, v52, v53
	v_cvt_pk_bf16_f32 v39, v54, v55
	v_mov_b32_e32 v220, v32
	v_mov_b32_e32 v221, v33
	v_mov_b32_e32 v222, v34
	v_mov_b32_e32 v223, v35
	v_mov_b32_dpp v32, v36 row_ror:8 row_mask:0xf bank_mask:0xc
	v_mov_b32_dpp v33, v37 row_ror:8 row_mask:0xf bank_mask:0xc
	v_mov_b32_dpp v34, v38 row_ror:8 row_mask:0xf bank_mask:0xc
	v_mov_b32_dpp v35, v39 row_ror:8 row_mask:0xf bank_mask:0xc
	v_mov_b32_dpp v36, v220 row_ror:8 row_mask:0xf bank_mask:0x3
	v_mov_b32_dpp v37, v221 row_ror:8 row_mask:0xf bank_mask:0x3
	v_mov_b32_dpp v38, v222 row_ror:8 row_mask:0xf bank_mask:0x3
	v_mov_b32_dpp v39, v223 row_ror:8 row_mask:0xf bank_mask:0x3
	v_lshl_add_u64 v[224:225], v[50:51], 0, s[62:63]
	global_store_dwordx4 v[50:51], v[32:35], off
	global_store_dwordx4 v[224:225], v[36:39], off
	global_load_dword v34, v[134:135], off offset:640
	v_lshl_add_u64 v[32:33], v[136:137], 0, s[18:19]
	s_waitcnt vmcnt(0)
; __device__ __forceinline__ u32x4 pack8(f32x4 a, f32x4 b) { u32x4 w; w[0] = cvt_pk_bf16(a[0], a[1]); w[1] = cvt_pk_bf16(a[2], a[3]); w[2] = cvt_pk_bf16(b[0], b[1]); w[3] = cvt_pk_bf16(b[2], b[3]); return w; }
;   __device__ __forceinline__ void operator()(const Acc& acc, const GUnit& u, int wr, int wc, int fr, int fq) const {
;     ...
;     for (int ai = 0; ai < 2; ++ai)
; #pragma unroll
;       for (int m = 0; m < 4; ++m) {
;         const int row = row0 + ai * 128 + m * 16;
;         const float rs = ss ? rsqrtf(ss[row] * (1.f / 2048.f) + EPS) : 1.f;
; #pragma unroll
;         for (int bj = 0; bj < 2; ++bj) *(u32x4*)(ob + (size_t)row * ld + bj * 128) = pack8(acc[ai][bj][m][0] * rs, acc[ai][bj][m][1] * rs);
	v_fmamk_f32 v34, v34, 0x3a000000, v144
	v_mul_f32_e32 v35, 0x4b800000, v34
	v_cmp_gt_f32_e32 vcc, s41, v34
	s_nop 1
	v_cndmask_b32_e32 v34, v34, v35, vcc
	v_rsq_f32_e32 v36, v34
	v_add_co_u32_e64 v34, s[4:5], s44, v136
	v_mul_f32_e32 v37, 0x45800000, v36
	v_cndmask_b32_e32 v36, v36, v37, vcc
	v_addc_co_u32_e64 v35, s[4:5], 0, v137, s[4:5]
	v_pk_mul_f32 v[30:31], v[30:31], v[36:37] op_sel_hi:[1,0]
	v_pk_mul_f32 v[28:29], v[28:29], v[36:37] op_sel_hi:[1,0]
	v_pk_mul_f32 v[26:27], v[26:27], v[36:37] op_sel_hi:[1,0]
	v_pk_mul_f32 v[24:25], v[24:25], v[36:37] op_sel_hi:[1,0]
	v_pk_mul_f32 v[22:23], v[22:23], v[36:37] op_sel_hi:[1,0]
	v_pk_mul_f32 v[20:21], v[20:21], v[36:37] op_sel_hi:[1,0]
	v_pk_mul_f32 v[38:39], v[18:19], v[36:37] op_sel_hi:[1,0]
	v_pk_mul_f32 v[36:37], v[16:17], v[36:37] op_sel_hi:[1,0]
	v_cvt_pk_bf16_f32 v16, v28, v29
	v_cvt_pk_bf16_f32 v17, v30, v31
	v_cvt_pk_bf16_f32 v18, v24, v25
	v_cvt_pk_bf16_f32 v19, v26, v27
	v_cvt_pk_bf16_f32 v20, v20, v21
	v_cvt_pk_bf16_f32 v21, v22, v23
	s_nop 0
	v_cvt_pk_bf16_f32 v22, v36, v37
	v_cvt_pk_bf16_f32 v23, v38, v39
	v_mov_b32_e32 v220, v16
	v_mov_b32_e32 v221, v17
	v_mov_b32_e32 v222, v18
	v_mov_b32_e32 v223, v19
	v_mov_b32_dpp v16, v20 row_ror:8 row_mask:0xf bank_mask:0xc
	v_mov_b32_dpp v17, v21 row_ror:8 row_mask:0xf bank_mask:0xc
	v_mov_b32_dpp v18, v22 row_ror:8 row_mask:0xf bank_mask:0xc
	v_mov_b32_dpp v19, v23 row_ror:8 row_mask:0xf bank_mask:0xc
	v_mov_b32_dpp v20, v220 row_ror:8 row_mask:0xf bank_mask:0x3
	v_mov_b32_dpp v21, v221 row_ror:8 row_mask:0xf bank_mask:0x3
	v_mov_b32_dpp v22, v222 row_ror:8 row_mask:0xf bank_mask:0x3
	v_mov_b32_dpp v23, v223 row_ror:8 row_mask:0xf bank_mask:0x3
	v_lshl_add_u64 v[224:225], v[34:35], 0, s[62:63]
	global_store_dwordx4 v[34:35], v[16:19], off
	global_store_dwordx4 v[224:225], v[20:23], off
	global_load_dword v18, v[134:135], off offset:704
	s_andn2_b64 vcc, exec, s[6:7]
	v_lshl_add_u64 v[16:17], v[136:137], 0, s[20:21]
	s_waitcnt vmcnt(0)
	v_fmamk_f32 v18, v18, 0x3a000000, v144
	v_mul_f32_e32 v19, 0x4b800000, v18
	v_cmp_gt_f32_e64 s[4:5], s41, v18
	s_nop 1
	v_cndmask_b32_e64 v18, v18, v19, s[4:5]
	v_rsq_f32_e32 v20, v18
	v_add_co_u32_e64 v18, s[6:7], s45, v136
	v_mul_f32_e32 v21, 0x45800000, v20
	v_cndmask_b32_e64 v20, v20, v21, s[4:5]
	v_addc_co_u32_e64 v19, s[6:7], 0, v137, s[6:7]
	v_pk_mul_f32 v[14:15], v[14:15], v[20:21] op_sel_hi:[1,0]
	v_pk_mul_f32 v[12:13], v[12:13], v[20:21] op_sel_hi:[1,0]
	v_pk_mul_f32 v[10:11], v[10:11], v[20:21] op_sel_hi:[1,0]
	v_pk_mul_f32 v[8:9], v[8:9], v[20:21] op_sel_hi:[1,0]
	v_pk_mul_f32 v[6:7], v[6:7], v[20:21] op_sel_hi:[1,0]
	v_pk_mul_f32 v[4:5], v[4:5], v[20:21] op_sel_hi:[1,0]
	v_pk_mul_f32 v[22:23], v[2:3], v[20:21] op_sel_hi:[1,0]
	v_pk_mul_f32 v[20:21], v[0:1], v[20:21] op_sel_hi:[1,0]
	v_cvt_pk_bf16_f32 v0, v12, v13
	v_cvt_pk_bf16_f32 v1, v14, v15
	v_cvt_pk_bf16_f32 v2, v8, v9
	v_cvt_pk_bf16_f32 v3, v10, v11
	s_mov_b64 s[4:5], -1
	v_cvt_pk_bf16_f32 v4, v4, v5
	v_cvt_pk_bf16_f32 v5, v6, v7
	v_cvt_pk_bf16_f32 v6, v20, v21
	v_cvt_pk_bf16_f32 v7, v22, v23
	v_mov_b32_e32 v220, v0
	v_mov_b32_e32 v221, v1
	v_mov_b32_e32 v222, v2
	v_mov_b32_e32 v223, v3
	v_mov_b32_dpp v0, v4 row_ror:8 row_mask:0xf bank_mask:0xc
	v_mov_b32_dpp v1, v5 row_ror:8 row_mask:0xf bank_mask:0xc
	v_mov_b32_dpp v2, v6 row_ror:8 row_mask:0xf bank_mask:0xc
	v_mov_b32_dpp v3, v7 row_ror:8 row_mask:0xf bank_mask:0xc
	v_mov_b32_dpp v4, v220 row_ror:8 row_mask:0xf bank_mask:0x3
	v_mov_b32_dpp v5, v221 row_ror:8 row_mask:0xf bank_mask:0x3
	v_mov_b32_dpp v6, v222 row_ror:8 row_mask:0xf bank_mask:0x3
	v_mov_b32_dpp v7, v223 row_ror:8 row_mask:0xf bank_mask:0x3
	v_lshl_add_u64 v[224:225], v[18:19], 0, s[62:63]
	global_store_dwordx4 v[18:19], v[0:3], off
	global_store_dwordx4 v[224:225], v[4:7], off
	s_cbranch_vccnz .LBB0_1117
	s_andn2_b64 vcc, exec, s[10:11]
	s_cbranch_vccnz .LBB0_1116
	s_barrier
	s_branch .LBB0_1116
